# v014 + diff-attention K/V tiles through a 3-stage LDS ring (two tiles in flight, counted vmcnt)
# baseline (speedup 1.0000x reference)
; #define LAS __attribute__((address_space(3)))
; __device__ __forceinline__ float ex2(float v) { return __builtin_amdgcn_exp2f(v); }
; #define MFMA32(a, b, c) __builtin_amdgcn_mfma_f32_32x32x16_bf16((a), (b), (c), 0, 0, 0)
; #define SCHEDB() __builtin_amdgcn_sched_barrier(0)
; __device__ __forceinline__ void diff_unit(const Params& p, LAS unsigned char* lds, int b, int h, int qb, float lam) {
;     ...
; #pragma unroll
;                 for (int r = 0; r < 16; ++r) s0[r] = ex2(s0[r]);
; #pragma unroll
;                 for (int g = 0; g < 4; ++g) {
;                     const int co = ((4 * (g >> 1) + (g & 1)) ^ xv) << 4;
;                     bf16x8 vf[4];
; #pragma unroll
;                     for (int db = 0; db < 4; ++db) vf[db] = *(const LAS bf16x8*)(vb + db * 4096 + co);
;                     const bf16x8 pf = pack8((g >> 1) ? s1 : s0, 8 * (g & 1));
; #pragma unroll
;                     for (int db = 0; db < 4; ++db) O[db] = MFMA32(pf, vf[db], O[db]);
;                     L = MFMA32(pf, ones, L);
;                     if (g < 2) {
; #pragma unroll
;                         for (int r = 0; r < 8; ++r) s1[8 * g + r] = ex2(s1[8 * g + r]);
;                     }
;                     SCHEDB();
;                 }
.LBB0_266:
	v_exp_f32_e32 v0, v112
	v_exp_f32_e32 v112, v113
	v_exp_f32_e32 v113, v114
	v_exp_f32_e32 v114, v115
	v_exp_f32_e32 v115, v116
	v_exp_f32_e32 v116, v117
	v_exp_f32_e32 v117, v118
	v_exp_f32_e32 v118, v119
	v_add_u32_e32 v132, v3, v198
	v_cvt_pk_bf16_f32 v112, v0, v112
	v_cvt_pk_bf16_f32 v113, v113, v114
	v_cvt_pk_bf16_f32 v114, v115, v116
	v_cvt_pk_bf16_f32 v115, v117, v118
	ds_read_b128 v[116:119], v132 offset:49152
	ds_read_b128 v[128:131], v132 offset:53248
	s_waitcnt lgkmcnt(1)
	v_mfma_f32_32x32x16_bf16 v[16:31], v[112:115], v[116:119], v[16:31]
	ds_read_b128 v[116:119], v132 offset:57344
	s_mov_b32 s10, s8
	s_mov_b32 s11, s8
	s_mov_b32 s9, s8
	v_exp_f32_e32 v0, v120
	v_exp_f32_e32 v120, v121
	v_exp_f32_e32 v121, v122
	s_waitcnt lgkmcnt(1)
	v_mfma_f32_32x32x16_bf16 v[32:47], v[112:115], v[128:131], v[32:47]
	ds_read_b128 v[128:131], v132 offset:61440
	v_exp_f32_e32 v122, v123
	v_exp_f32_e32 v123, v124
	v_exp_f32_e32 v124, v125
	v_exp_f32_e32 v125, v126
	v_exp_f32_e32 v126, v127
	v_exp_f32_e32 v127, v96
	s_waitcnt lgkmcnt(1)
	v_mfma_f32_32x32x16_bf16 v[48:63], v[112:115], v[116:119], v[48:63]
	v_mov_b64_e32 v[118:119], s[10:11]
	v_mov_b64_e32 v[116:117], s[8:9]
	v_exp_f32_e32 v132, v101
	v_exp_f32_e32 v133, v102
	v_exp_f32_e32 v134, v103
	s_waitcnt lgkmcnt(0)
	v_mfma_f32_32x32x16_bf16 v[64:79], v[112:115], v[128:131], v[64:79]
	v_exp_f32_e32 v128, v97
	v_exp_f32_e32 v129, v98
	v_exp_f32_e32 v130, v99
	v_exp_f32_e32 v131, v100
	v_mfma_f32_32x32x16_bf16 v[80:95], v[112:115], v[116:119], v[80:95]
	v_add_u32_e32 v135, v3, v199
	v_cvt_pk_bf16_f32 v96, v0, v120
	v_cvt_pk_bf16_f32 v97, v121, v122
	v_cvt_pk_bf16_f32 v98, v123, v124
	v_cvt_pk_bf16_f32 v99, v125, v126
	ds_read_b128 v[100:103], v135 offset:49152
	ds_read_b128 v[112:115], v135 offset:53248
	s_waitcnt lgkmcnt(1)
	v_mfma_f32_32x32x16_bf16 v[16:31], v[96:99], v[100:103], v[16:31]
	v_exp_f32_e32 v0, v104
	v_exp_f32_e32 v108, v108
	v_exp_f32_e32 v109, v109
	v_exp_f32_e32 v110, v110
	v_exp_f32_e32 v111, v111
	s_waitcnt lgkmcnt(0)
	v_mfma_f32_32x32x16_bf16 v[32:47], v[96:99], v[112:115], v[32:47]
	ds_read_b128 v[100:103], v135 offset:57344
	ds_read_b128 v[112:115], v135 offset:61440
	s_waitcnt lgkmcnt(1)
	v_mfma_f32_32x32x16_bf16 v[48:63], v[96:99], v[100:103], v[48:63]
	s_waitcnt lgkmcnt(0)
	v_mfma_f32_32x32x16_bf16 v[64:79], v[96:99], v[112:115], v[64:79]
	v_exp_f32_e32 v112, v105
	v_exp_f32_e32 v113, v106
	v_exp_f32_e32 v114, v107
	v_mfma_f32_32x32x16_bf16 v[80:95], v[96:99], v[116:119], v[80:95]
	v_add_u32_e32 v115, v3, v200
	v_cvt_pk_bf16_f32 v96, v127, v128
	v_cvt_pk_bf16_f32 v97, v129, v130
	v_cvt_pk_bf16_f32 v98, v131, v132
	v_cvt_pk_bf16_f32 v99, v133, v134
	ds_read_b128 v[100:103], v115 offset:49152
	ds_read_b128 v[104:107], v115 offset:53248
	s_waitcnt lgkmcnt(1)
	v_mfma_f32_32x32x16_bf16 v[16:31], v[96:99], v[100:103], v[16:31]
	s_waitcnt lgkmcnt(0)
	v_mfma_f32_32x32x16_bf16 v[32:47], v[96:99], v[104:107], v[32:47]
	ds_read_b128 v[100:103], v115 offset:57344
	ds_read_b128 v[104:107], v115 offset:61440
	s_waitcnt lgkmcnt(1)
	v_mfma_f32_32x32x16_bf16 v[48:63], v[96:99], v[100:103], v[48:63]
	s_waitcnt lgkmcnt(0)
	v_mfma_f32_32x32x16_bf16 v[64:79], v[96:99], v[104:107], v[64:79]
	v_mfma_f32_32x32x16_bf16 v[80:95], v[96:99], v[116:119], v[80:95]
	v_add_u32_e32 v115, v3, v201
	v_cvt_pk_bf16_f32 v96, v0, v112
	v_cvt_pk_bf16_f32 v97, v113, v114
	v_cvt_pk_bf16_f32 v98, v108, v109
	v_cvt_pk_bf16_f32 v99, v110, v111
	ds_read_b128 v[100:103], v115 offset:49152
	ds_read_b128 v[104:107], v115 offset:53248
	s_waitcnt lgkmcnt(1)
	v_mfma_f32_32x32x16_bf16 v[16:31], v[96:99], v[100:103], v[16:31]
	s_waitcnt lgkmcnt(0)
	v_mfma_f32_32x32x16_bf16 v[32:47], v[96:99], v[104:107], v[32:47]
	ds_read_b128 v[100:103], v115 offset:57344
	ds_read_b128 v[104:107], v115 offset:61440
	s_waitcnt lgkmcnt(1)
	v_mfma_f32_32x32x16_bf16 v[48:63], v[96:99], v[100:103], v[48:63]
	s_waitcnt lgkmcnt(0)
	v_mfma_f32_32x32x16_bf16 v[64:79], v[96:99], v[104:107], v[64:79]
	v_mfma_f32_32x32x16_bf16 v[80:95], v[96:99], v[116:119], v[80:95]

; __device__ __forceinline__ void diff_unit(const Params& p, LAS unsigned char* lds, int b, int h, int qb, float lam) {
;     ...
;         const bf16_t* Kg0 = (const bf16_t*)(p.ws + WS_KD) + ((size_t)(2 * h + mp) * MT + rowbase) * 64;
;         tile_dma<64>(Kg0, Vg0, lds + A_KOFF, lds + A_VOFF, wid, lane);
;         const bf16_t* qp = QK + (rowbase + q0 + c) * 4096 + h * 128 + 64 * mp + hh * 8;
;         bf16x8 qf[4];
; #pragma unroll
;         for (int ks = 0; ks < 4; ++ks) qf[ks] = *(const bf16x8*)(qp + 16 * ks);
; #pragma unroll
;         for (int db = 0; db < 4; ++db) O[db] = (f32x16){};
;         f32x16 L = (f32x16){};
;         f32x16 negm = (f32x16){};
;         float m = 0.f;
;         asm volatile("s_waitcnt vmcnt(0)" ::: "memory");
;         __syncthreads();
;         for (int jt = 0; jt < NT; ++jt) {
;             const int cur = jt & 1;
;             if (jt + 1 < NT) tile_dma<64>(Kg0 + (size_t)(jt + 1) * 4096, Vg0 + (size_t)(jt + 1) * 8192, lds + A_KOFF + (cur ^ 1) * A_KBUF, lds + A_VOFF + (cur ^ 1) * A_VBUF, wid, lane);
.LBB0_282:
	s_lshl_b32 s75, s0, 7
	s_lshl_b32 s0, s72, 21
	v_sub_u32_e32 v2, v196, v112
	s_and_b32 s9, s0, 0x3800000
	s_lshl_b32 s0, s72, 15
	v_subrev_u32_e32 v208, 64, v2
	v_add_u32_e32 v2, s23, v117
	s_and_b32 s6, s0, 0x700000
	v_ashrrev_i32_e32 v3, 31, v2
	s_or_b32 s6, s9, s6
	v_lshlrev_b64 v[4:5], 7, v[2:3]
	v_lshl_add_u64 v[4:5], s[6:7], 0, v[4:5]
	v_and_b32_e32 v3, 7, v118
	v_add_u32_e32 v2, 8, v2
	v_lshl_or_b32 v4, v3, 4, v4
	v_ashrrev_i32_e32 v3, 31, v2
	v_lshlrev_b64 v[2:3], 7, v[2:3]
	v_lshl_add_u64 v[166:167], s[20:21], 0, v[4:5]
	v_lshl_add_u64 v[2:3], s[6:7], 0, v[2:3]
	v_and_b32_e32 v4, 7, v119
	s_add_i32 s3, s22, s3
	s_lshl_b32 s0, s72, 14
	v_lshl_or_b32 v2, v4, 4, v2
	s_add_i32 s3, s3, s1
	s_and_b32 s10, s0, 0x380000
	v_lshl_add_u64 v[168:169], s[20:21], 0, v[2:3]
	v_add_u32_e32 v2, s3, v114
	s_or_b32 s6, s9, s10
	v_add_lshl_u32 v2, v2, v115, 7
	v_mov_b32_e32 v3, v1
	s_waitcnt vmcnt(0)
	s_mov_b32 s67, s7
	v_lshl_add_u64 v[180:181], s[6:7], 0, v[2:3]
	v_and_b32_e32 v2, 7, v116
	s_lshl_b64 s[4:5], s[66:67], 16
	v_lshl_or_b32 v180, v2, 4, v180
	v_lshlrev_b32_e32 v0, 6, v120
	s_lshl_b32 s80, s88, 11
	s_or_b32 s0, s4, 0x8000
	v_lshl_add_u64 v[2:3], s[38:39], 0, v[180:181]
	s_mov_b32 s1, 1
	s_mov_b64 s[4:5], 0
	s_mov_b32 s3, s77
	s_mov_b32 s96, 0
	s_movk_i32 s97, 0x4000
	s_mov_b32 s98, 0x11000
	s_add_i32 m0, s78, s98
	s_add_i32 s9, s98, s80
	global_load_lds_dwordx4 v[2:3], off
	s_add_i32 m0, s9, 0x8000
	s_add_i32 s9, s98, s79
	global_load_lds_dwordx4 v[166:167], off
	s_add_i32 m0, s9, 0x8000
	v_lshl_add_u64 v[2:3], v[2:3], 0, s[42:43]
	global_load_lds_dwordx4 v[168:169], off
	s_waitcnt vmcnt(3) lgkmcnt(0)
	s_barrier
	s_branch .LBB0_285

; #define LAS __attribute__((address_space(3)))
; #define MFMA32(a, b, c) __builtin_amdgcn_mfma_f32_32x32x16_bf16((a), (b), (c), 0, 0, 0)
; #define SCHEDB() __builtin_amdgcn_sched_barrier(0)
; __device__ __forceinline__ void diff_unit(const Params& p, LAS unsigned char* lds, int b, int h, int qb, float lam) {
;     ...
;         for (int jt = 0; jt < NT; ++jt) {
;             const int cur = jt & 1;
;             if (jt + 1 < NT) tile_dma<64>(Kg0 + (size_t)(jt + 1) * 4096, Vg0 + (size_t)(jt + 1) * 8192, lds + A_KOFF + (cur ^ 1) * A_KBUF, lds + A_VOFF + (cur ^ 1) * A_VBUF, wid, lane);
;             if (jt <= mylast) {
;                 const LAS unsigned char* kb = lds + A_KOFF + cur * A_KBUF + c * 128;
;                 const LAS unsigned char* vb = lds + A_VOFF + cur * A_VBUF + c * 128;
;                 f32x16 s0, s1;
;                 {
;                     bf16x8 a[2][2];
;                     { const int co = (0 ^ xk) << 4; a[0][0] = *(const LAS bf16x8*)(kb + co); a[0][1] = *(const LAS bf16x8*)(kb + 4096 + co); }
; #pragma unroll
;                     for (int ks = 0; ks < 4; ++ks) {
;                         if (ks + 1 < 4) { const int co = ((2 * (ks + 1)) ^ xk) << 4; a[(ks + 1) & 1][0] = *(const LAS bf16x8*)(kb + co); a[(ks + 1) & 1][1] = *(const LAS bf16x8*)(kb + 4096 + co); }
;                         if (ks == 0) { s0 = MFMA32(a[0][0], qf[0], negm); s1 = MFMA32(a[0][1], qf[0], negm); }
;                         else { s0 = MFMA32(a[ks & 1][0], qf[ks], s0); s1 = MFMA32(a[ks & 1][1], qf[ks], s1); }
;                         SCHEDB();
;                     }
;                 }
;                 if ((q0 - (64 * jt + 63)) < 91) {
;                     const int idx0 = (q0 + c) - (64 * jt + 16 * hh) + 64;
; #pragma unroll
;                     for (int r = 0; r < 16; ++r) { s0[r] += tab[min(idx0 - r, 255)]; s1[r] += tab[min(idx0 - 32 - r, 255)]; if ((r & 3) == 3) SCHEDB(); }
;                 }
.LBB0_284:
	s_sub_i32 s3, s3, 64
	s_add_i32 s1, s1, 1
	s_cmp_eq_u32 s0, s4
	v_lshl_add_u64 v[2:3], v[2:3], 0, s[42:43]
	s_cbranch_scc1 .Lring0_last
	s_waitcnt vmcnt(3) lgkmcnt(0)
	s_barrier
	s_branch .LBB0_285
.Lring0_last:
	s_waitcnt vmcnt(0) lgkmcnt(0)
	s_barrier
	s_branch .LBB0_290
.LBB0_285:
	s_mov_b64 s[10:11], s[4:5]
	s_add_u32 s4, s10, 0x4000
	s_addc_u32 s5, s11, 0
	s_mov_b32 s22, s96
	s_mov_b32 s96, s97
	s_mov_b32 s97, s98
	s_mov_b32 s98, s22
	s_mov_b32 s6, s96
	s_cmp_eq_u32 s0, s4
	s_cbranch_scc1 .Lring0_nodma
	s_add_i32 m0, s78, s22
	s_add_i32 s9, s22, s80
	global_load_lds_dwordx4 v[2:3], off
	v_lshl_add_u64 v[4:5], v[166:167], 0, s[4:5]
	s_add_i32 m0, s9, 0x8000
	s_add_i32 s9, s22, s79
	global_load_lds_dwordx4 v[4:5], off
	v_lshl_add_u64 v[4:5], v[168:169], 0, s[4:5]
	s_add_i32 m0, s9, 0x8000
	s_nop 0
	global_load_lds_dwordx4 v[4:5], off
.Lring0_nodma:
	s_cmp_gt_i32 s1, s76
	s_cbranch_scc1 .LBB0_284
	v_add_u32_e32 v4, s6, v197
	v_add_u32_e32 v5, v4, v203
	ds_read_b128 v[6:9], v5
	ds_read_b128 v[10:13], v5 offset:4096
	v_add_u32_e32 v5, v4, v205
	s_waitcnt lgkmcnt(0)
	v_mfma_f32_32x32x16_bf16 v[128:143], v[6:9], v[156:159], v[96:111]
	ds_read_b128 v[6:9], v5
	ds_read_b128 v[184:187], v5 offset:4096
	v_mfma_f32_32x32x16_bf16 v[112:127], v[10:13], v[156:159], v[96:111]
	s_waitcnt lgkmcnt(0)
	v_mfma_f32_32x32x16_bf16 v[128:143], v[6:9], v[152:155], v[128:143]
	v_add_u32_e32 v5, v4, v206
	ds_read_b128 v[6:9], v5
	ds_read_b128 v[10:13], v5 offset:4096
	v_mfma_f32_32x32x16_bf16 v[112:127], v[184:187], v[152:155], v[112:127]
	s_waitcnt lgkmcnt(0)
	v_mfma_f32_32x32x16_bf16 v[128:143], v[6:9], v[148:151], v[128:143]
	v_add_u32_e32 v5, v4, v207
	ds_read_b128 v[6:9], v5
	ds_read_b128 v[184:187], v5 offset:4096
	v_mfma_f32_32x32x16_bf16 v[112:127], v[10:13], v[148:151], v[112:127]
	s_waitcnt lgkmcnt(0)
	v_mfma_f32_32x32x16_bf16 v[128:143], v[6:9], v[144:147], v[128:143]
	v_mfma_f32_32x32x16_bf16 v[112:127], v[184:187], v[144:147], v[112:127]
	s_add_i32 s6, s3, 0xffffff81
	s_cmpk_gt_i32 s6, 0x5a
	s_cbranch_scc1 .LBB0_288
	v_add_u32_e32 v5, s3, v208
	s_add_i32 s6, 0, 0x10000
	v_min_i32_e32 v8, 0xc0, v5
	v_lshl_add_u32 v9, v8, 2, s6
	v_min_i32_e32 v8, 0xe0, v5
	v_lshl_add_u32 v10, v8, 2, s6
	v_min_i32_e32 v8, 0xc1, v5
	v_lshl_add_u32 v11, v8, 2, s6
	v_min_i32_e32 v8, 0xe1, v5
	v_min_i32_e32 v6, 0xbf, v5
	v_min_i32_e32 v7, 0xdf, v5
	v_lshl_add_u32 v12, v8, 2, s6
	v_min_i32_e32 v8, 0xc2, v5
	v_lshl_add_u32 v6, v6, 2, s6
	v_lshl_add_u32 v7, v7, 2, s6
	v_lshl_add_u32 v13, v8, 2, s6
	v_min_i32_e32 v8, 0xe2, v5
	v_lshl_add_u32 v14, v8, 2, s6
	ds_read_b32 v6, v6 offset:256
	ds_read_b32 v8, v7 offset:128
	ds_read_b32 v7, v9 offset:252
	ds_read_b32 v9, v10 offset:124
	ds_read_b32 v10, v11 offset:248
	ds_read_b32 v12, v12 offset:120
	ds_read_b32 v11, v13 offset:244
	ds_read_b32 v13, v14 offset:116
	v_min_i32_e32 v184, 0xe4, v5
	v_lshl_add_u32 v185, v184, 2, s6
	v_min_i32_e32 v184, 0xc5, v5
	v_lshl_add_u32 v186, v184, 2, s6
	v_min_i32_e32 v184, 0xe5, v5
	v_min_i32_e32 v14, 0xc3, v5
	v_min_i32_e32 v15, 0xe3, v5
	v_lshl_add_u32 v187, v184, 2, s6
	v_min_i32_e32 v184, 0xc6, v5
	v_lshl_add_u32 v14, v14, 2, s6
	v_lshl_add_u32 v15, v15, 2, s6
	v_min_i32_e32 v183, 0xc4, v5
	v_lshl_add_u32 v189, v184, 2, s6
	v_min_i32_e32 v184, 0xe6, v5
	v_lshl_add_u32 v183, v183, 2, s6
	v_lshl_add_u32 v209, v184, 2, s6
	ds_read_b32 v14, v14 offset:240
	ds_read_b32 v184, v15 offset:112
	ds_read_b32 v15, v183 offset:236
	ds_read_b32 v185, v185 offset:108
	ds_read_b32 v186, v186 offset:232
	ds_read_b32 v188, v187 offset:104
	ds_read_b32 v187, v189 offset:228
	ds_read_b32 v189, v209 offset:100
	v_min_i32_e32 v210, 0xc8, v5
	v_lshl_add_u32 v211, v210, 2, s6
	v_min_i32_e32 v210, 0xe8, v5
	v_lshl_add_u32 v213, v210, 2, s6
	v_min_i32_e32 v210, 0xc9, v5
	v_lshl_add_u32 v214, v210, 2, s6
	v_min_i32_e32 v210, 0xe9, v5
	v_min_i32_e32 v183, 0xc7, v5
	v_lshl_add_u32 v215, v210, 2, s6
	v_min_i32_e32 v210, 0xca, v5
	v_lshl_add_u32 v183, v183, 2, s6
	v_min_i32_e32 v209, 0xe7, v5
	v_lshl_add_u32 v217, v210, 2, s6
	v_min_i32_e32 v210, 0xea, v5
	v_lshl_add_u32 v209, v209, 2, s6
	v_lshl_add_u32 v218, v210, 2, s6
	ds_read_b32 v210, v183 offset:224
	ds_read_b32 v212, v209 offset:96
	ds_read_b32 v211, v211 offset:220
	ds_read_b32 v213, v213 offset:92
	ds_read_b32 v214, v214 offset:216
	ds_read_b32 v216, v215 offset:88
	ds_read_b32 v215, v217 offset:212
	ds_read_b32 v217, v218 offset:84
	v_min_i32_e32 v183, 0xcb, v5
	v_lshl_add_u32 v183, v183, 2, s6
	v_min_i32_e32 v209, 0xeb, v5
	v_min_i32_e32 v218, 0xcc, v5
	v_min_i32_e32 v219, 0xec, v5
	v_min_i32_e32 v220, 0xcd, v5
	v_min_i32_e32 v221, 0xed, v5
	v_min_i32_e32 v222, 0xce, v5
	v_min_i32_e32 v5, 0xee, v5
	v_lshl_add_u32 v209, v209, 2, s6
	v_lshl_add_u32 v218, v218, 2, s6
	v_lshl_add_u32 v219, v219, 2, s6
	v_lshl_add_u32 v220, v220, 2, s6
	v_lshl_add_u32 v221, v221, 2, s6
	v_lshl_add_u32 v222, v222, 2, s6
	s_waitcnt lgkmcnt(0)
	v_pk_add_f32 v[130:131], v[130:131], v[10:11]
	v_pk_add_f32 v[128:129], v[128:129], v[6:7]
	v_pk_add_f32 v[134:135], v[134:135], v[186:187]
	v_pk_add_f32 v[132:133], v[132:133], v[14:15]
	v_lshl_add_u32 v5, v5, 2, s6
	ds_read_b32 v6, v183 offset:208
	ds_read_b32 v10, v209 offset:80
	ds_read_b32 v14, v220 offset:200
	ds_read_b32 v15, v222 offset:196
	ds_read_b32 v7, v218 offset:204
	ds_read_b32 v187, v5 offset:68
	ds_read_b32 v186, v221 offset:72
	ds_read_b32 v11, v219 offset:76
	v_pk_add_f32 v[138:139], v[138:139], v[214:215]
	v_pk_add_f32 v[136:137], v[136:137], v[210:211]
	s_waitcnt lgkmcnt(0)
	v_pk_add_f32 v[142:143], v[142:143], v[14:15]
	v_pk_add_f32 v[140:141], v[140:141], v[6:7]
	v_pk_add_f32 v[114:115], v[114:115], v[12:13]
	v_pk_add_f32 v[112:113], v[112:113], v[8:9]
	v_pk_add_f32 v[118:119], v[118:119], v[188:189]
	v_pk_add_f32 v[116:117], v[116:117], v[184:185]
	v_pk_add_f32 v[122:123], v[122:123], v[216:217]
	v_pk_add_f32 v[120:121], v[120:121], v[212:213]
	v_pk_add_f32 v[126:127], v[126:127], v[186:187]
	v_pk_add_f32 v[124:125], v[124:125], v[10:11]

; #define LAS __attribute__((address_space(3)))
; #define MFMA32(a, b, c) __builtin_amdgcn_mfma_f32_32x32x16_bf16((a), (b), (c), 0, 0, 0)
; #define SCHEDB() __builtin_amdgcn_sched_barrier(0)
; __device__ __forceinline__ void diff_unit(const Params& p, LAS unsigned char* lds, int b, int h, int qb, float lam) {
;     ...
;             if (jt <= mylast) {
;                 const LAS unsigned char* kb = lds + A_KOFF + cur * A_KBUF + c * 128;
;                 const LAS unsigned char* vb = lds + A_VOFF + cur * A_VBUF + c * 128;
;                 f32x16 s0, s1;
;                 {
;                     bf16x8 a[2][2];
;                     { const int co = (0 ^ xk) << 4; a[0][0] = *(const LAS bf16x8*)(kb + co); a[0][1] = *(const LAS bf16x8*)(kb + 4096 + co); }
; #pragma unroll
;                     for (int ks = 0; ks < 4; ++ks) {
;                         if (ks + 1 < 4) { const int co = ((2 * (ks + 1)) ^ xk) << 4; a[(ks + 1) & 1][0] = *(const LAS bf16x8*)(kb + co); a[(ks + 1) & 1][1] = *(const LAS bf16x8*)(kb + 4096 + co); }
;                         if (ks == 0) { s0 = MFMA32(a[0][0], qf[0], negm); s1 = MFMA32(a[0][1], qf[0], negm); }
;                         else { s0 = MFMA32(a[ks & 1][0], qf[ks], s0); s1 = MFMA32(a[ks & 1][1], qf[ks], s1); }
;                         SCHEDB();
;                     }
;                 }
;                 if ((q0 - (64 * jt + 63)) < 91) {
;                     const int idx0 = (q0 + c) - (64 * jt + 16 * hh) + 64;
; #pragma unroll
;                     for (int r = 0; r < 16; ++r) { s0[r] += tab[min(idx0 - r, 255)]; s1[r] += tab[min(idx0 - 32 - r, 255)]; if ((r & 3) == 3) SCHEDB(); }
;                 }
.LBB0_290:
	s_lshl_b32 s66, s66, 2
	s_or_b32 s0, s66, 2
	s_sub_i32 s5, s77, 63
	s_cmp_ge_i32 s0, s76
	s_cbranch_scc1 .LBB0_296
	s_add_i32 s0, s66, 3
	s_lshl_b32 s1, s0, 14
	s_mov_b32 s1, s97
	v_add_u32_e32 v2, s1, v197
	v_add_u32_e32 v3, v2, v203
	ds_read_b128 v[4:7], v3
	ds_read_b128 v[8:11], v3 offset:4096
	v_add_u32_e32 v3, v2, v205
	s_waitcnt lgkmcnt(1)
	v_mfma_f32_32x32x16_bf16 v[112:127], v[4:7], v[156:159], v[96:111]
	ds_read_b128 v[4:7], v3
	ds_read_b128 v[12:15], v3 offset:4096
	s_waitcnt lgkmcnt(2)
	v_mfma_f32_32x32x16_bf16 v[96:111], v[8:11], v[156:159], v[96:111]
	s_waitcnt lgkmcnt(1)
	v_mfma_f32_32x32x16_bf16 v[112:127], v[4:7], v[152:155], v[112:127]
	v_add_u32_e32 v3, v2, v206
	ds_read_b128 v[4:7], v3
	ds_read_b128 v[8:11], v3 offset:4096
	s_waitcnt lgkmcnt(2)
	v_mfma_f32_32x32x16_bf16 v[96:111], v[12:15], v[152:155], v[96:111]
	s_waitcnt lgkmcnt(1)
	v_mfma_f32_32x32x16_bf16 v[112:127], v[4:7], v[148:151], v[112:127]
	v_add_u32_e32 v3, v2, v207
	ds_read_b128 v[4:7], v3
	ds_read_b128 v[12:15], v3 offset:4096
	s_waitcnt lgkmcnt(2)
	v_mfma_f32_32x32x16_bf16 v[96:111], v[8:11], v[148:151], v[96:111]
	s_waitcnt lgkmcnt(1)
	v_mfma_f32_32x32x16_bf16 v[112:127], v[4:7], v[144:147], v[112:127]
	s_waitcnt lgkmcnt(0)
	v_mfma_f32_32x32x16_bf16 v[96:111], v[12:15], v[144:147], v[96:111]
	s_lshl_b32 s0, s0, 6
	s_sub_i32 s1, s5, s0
	s_cmpk_gt_i32 s1, 0x5a
	s_cbranch_scc1 .LBB0_293
	s_sub_i32 s0, 0, s0
	v_add_u32_e32 v3, s0, v202
	s_add_i32 s0, 0, 0x10000
	v_min_i32_e32 v6, 0xc0, v3
	v_lshl_add_u32 v7, v6, 2, s0
	v_min_i32_e32 v6, 0xe0, v3
	v_lshl_add_u32 v8, v6, 2, s0
	v_min_i32_e32 v6, 0xc1, v3
	v_lshl_add_u32 v9, v6, 2, s0
	v_min_i32_e32 v6, 0xe1, v3
	v_min_i32_e32 v4, 0xbf, v3
	v_min_i32_e32 v5, 0xdf, v3
	v_lshl_add_u32 v10, v6, 2, s0
	v_min_i32_e32 v6, 0xc2, v3
	v_lshl_add_u32 v4, v4, 2, s0
	v_lshl_add_u32 v5, v5, 2, s0
	v_lshl_add_u32 v11, v6, 2, s0
	v_min_i32_e32 v6, 0xe2, v3
	v_lshl_add_u32 v12, v6, 2, s0
	ds_read_b32 v4, v4 offset:256
	ds_read_b32 v6, v5 offset:128
	ds_read_b32 v5, v7 offset:252
	ds_read_b32 v7, v8 offset:124
	ds_read_b32 v8, v9 offset:248
	ds_read_b32 v10, v10 offset:120
	ds_read_b32 v9, v11 offset:244
	ds_read_b32 v11, v12 offset:116
	v_min_i32_e32 v14, 0xc4, v3
	v_lshl_add_u32 v15, v14, 2, s0
	v_min_i32_e32 v14, 0xe4, v3
	v_lshl_add_u32 v128, v14, 2, s0
	v_min_i32_e32 v14, 0xc5, v3
	v_lshl_add_u32 v129, v14, 2, s0
	v_min_i32_e32 v14, 0xe5, v3
	v_min_i32_e32 v12, 0xc3, v3
	v_min_i32_e32 v13, 0xe3, v3
	v_lshl_add_u32 v130, v14, 2, s0
	v_min_i32_e32 v14, 0xc6, v3
	v_lshl_add_u32 v12, v12, 2, s0
	v_lshl_add_u32 v13, v13, 2, s0
	v_lshl_add_u32 v131, v14, 2, s0
	v_min_i32_e32 v14, 0xe6, v3
	v_lshl_add_u32 v132, v14, 2, s0
	ds_read_b32 v12, v12 offset:240
	ds_read_b32 v14, v13 offset:112
	ds_read_b32 v13, v15 offset:236
	ds_read_b32 v15, v128 offset:108
	ds_read_b32 v128, v129 offset:232
	ds_read_b32 v130, v130 offset:104
	ds_read_b32 v129, v131 offset:228
	ds_read_b32 v131, v132 offset:100
	v_min_i32_e32 v134, 0xc8, v3
	v_lshl_add_u32 v135, v134, 2, s0
	v_min_i32_e32 v134, 0xe8, v3
	v_lshl_add_u32 v136, v134, 2, s0
	v_min_i32_e32 v134, 0xc9, v3
	v_lshl_add_u32 v137, v134, 2, s0
	v_min_i32_e32 v134, 0xe9, v3
	v_min_i32_e32 v132, 0xc7, v3
	v_min_i32_e32 v133, 0xe7, v3
	v_lshl_add_u32 v138, v134, 2, s0
	v_min_i32_e32 v134, 0xca, v3
	v_lshl_add_u32 v132, v132, 2, s0
	v_lshl_add_u32 v133, v133, 2, s0
	v_lshl_add_u32 v139, v134, 2, s0
	v_min_i32_e32 v134, 0xea, v3
	v_lshl_add_u32 v140, v134, 2, s0
	ds_read_b32 v132, v132 offset:224
	ds_read_b32 v134, v133 offset:96
	ds_read_b32 v133, v135 offset:220
	ds_read_b32 v135, v136 offset:92
	ds_read_b32 v136, v137 offset:216
	ds_read_b32 v138, v138 offset:88
	ds_read_b32 v137, v139 offset:212
	ds_read_b32 v139, v140 offset:84
	v_min_i32_e32 v140, 0xcb, v3
	v_lshl_add_u32 v140, v140, 2, s0
	v_min_i32_e32 v141, 0xeb, v3
	v_min_i32_e32 v142, 0xcc, v3
	v_min_i32_e32 v143, 0xec, v3
	v_min_i32_e32 v144, 0xcd, v3
	v_min_i32_e32 v145, 0xed, v3
	v_min_i32_e32 v146, 0xce, v3
	v_min_i32_e32 v3, 0xee, v3
	v_lshl_add_u32 v141, v141, 2, s0
	v_lshl_add_u32 v142, v142, 2, s0
	v_lshl_add_u32 v143, v143, 2, s0
	v_lshl_add_u32 v144, v144, 2, s0
	v_lshl_add_u32 v145, v145, 2, s0
	v_lshl_add_u32 v146, v146, 2, s0
	s_waitcnt lgkmcnt(14)
	v_pk_add_f32 v[114:115], v[114:115], v[8:9]
	v_pk_add_f32 v[112:113], v[112:113], v[4:5]
	s_waitcnt lgkmcnt(9)
	v_pk_add_f32 v[118:119], v[118:119], v[128:129]
	v_pk_add_f32 v[116:117], v[116:117], v[12:13]
	v_lshl_add_u32 v3, v3, 2, s0
	ds_read_b32 v4, v140 offset:208
	ds_read_b32 v8, v141 offset:80
	ds_read_b32 v12, v144 offset:200
	ds_read_b32 v13, v146 offset:196
	ds_read_b32 v5, v142 offset:204
	ds_read_b32 v129, v3 offset:68
	ds_read_b32 v128, v145 offset:72
	ds_read_b32 v9, v143 offset:76
	s_waitcnt lgkmcnt(9)
	v_pk_add_f32 v[122:123], v[122:123], v[136:137]
	v_pk_add_f32 v[120:121], v[120:121], v[132:133]
	s_waitcnt lgkmcnt(4)
	v_pk_add_f32 v[126:127], v[126:127], v[12:13]
	s_waitcnt lgkmcnt(3)
	v_pk_add_f32 v[124:125], v[124:125], v[4:5]
	v_pk_add_f32 v[98:99], v[98:99], v[10:11]
	v_pk_add_f32 v[96:97], v[96:97], v[6:7]
	v_pk_add_f32 v[102:103], v[102:103], v[130:131]
	v_pk_add_f32 v[100:101], v[100:101], v[14:15]
	v_pk_add_f32 v[106:107], v[106:107], v[138:139]
	v_pk_add_f32 v[104:105], v[104:105], v[134:135]
	s_waitcnt lgkmcnt(1)
	v_pk_add_f32 v[110:111], v[110:111], v[128:129]
	s_waitcnt lgkmcnt(0)
	v_pk_add_f32 v[108:109], v[108:109], v[8:9]

; __device__ __forceinline__ unsigned cvtpk(float lo, float hi) { f32x2_t v = {lo, hi}; bf16x2_t b = __builtin_convertvector(v, bf16x2_t); return __builtin_bit_cast(unsigned, b); }
; __device__ __forceinline__ void diff_unit(const Params& p, LAS unsigned char* lds, int b, int h, int qb, float lam) {
;     ...
;         const bf16_t* Kg0 = (const bf16_t*)(p.ws + WS_KD) + ((size_t)(2 * h + mp) * MT + rowbase) * 64;
;         tile_dma<64>(Kg0, Vg0, lds + A_KOFF, lds + A_VOFF, wid, lane);
;         const bf16_t* qp = QK + (rowbase + q0 + c) * 4096 + h * 128 + 64 * mp + hh * 8;
;         bf16x8 qf[4];
; #pragma unroll
;         for (int ks = 0; ks < 4; ++ks) qf[ks] = *(const bf16x8*)(qp + 16 * ks);
; #pragma unroll
;         for (int db = 0; db < 4; ++db) O[db] = (f32x16){};
;         f32x16 L = (f32x16){};
;         f32x16 negm = (f32x16){};
;         float m = 0.f;
;         asm volatile("s_waitcnt vmcnt(0)" ::: "memory");
;         __syncthreads();
;     ...
;         if (mp == 0) {
; #pragma unroll
;             for (int db = 0; db < 4; ++db)
; #pragma unroll
;                 for (int j = 0; j < 8; ++j) park[(db * 8 + j) * 64] = cvtpk(O[db][2 * j], O[db][2 * j + 1]);
;         }
.LBB0_302:
	s_mov_b64 s[0:1], 0x1000
	v_lshl_add_u64 v[186:187], v[164:165], 0, s[0:1]
	s_mov_b64 s[0:1], 0x1100
	v_lshl_add_u64 v[4:5], v[164:165], 0, s[0:1]
	s_mov_b64 s[0:1], 0x1200
	v_lshl_add_u64 v[6:7], v[164:165], 0, s[0:1]
	s_mov_b64 s[0:1], 0x1300
	v_lshl_add_u64 v[176:177], v[164:165], 0, s[0:1]
	s_mov_b64 s[0:1], 0x1400
	v_lshl_add_u64 v[178:179], v[164:165], 0, s[0:1]
	s_mov_b64 s[0:1], 0x1500
	v_lshl_add_u64 v[182:183], v[164:165], 0, s[0:1]
	s_mov_b64 s[0:1], 0x1600
	v_lshl_add_u64 v[184:185], v[164:165], 0, s[0:1]
	s_mov_b64 s[0:1], 0x1700
	v_lshl_add_u64 v[8:9], v[164:165], 0, s[0:1]
	s_mov_b64 s[0:1], 0x1800
	s_waitcnt vmcnt(0)
	v_lshl_add_u64 v[188:189], v[164:165], 0, s[0:1]
	s_mov_b64 s[0:1], 0x1900
	v_lshl_add_u64 v[10:11], v[164:165], 0, s[0:1]
	v_lshl_add_u64 v[12:13], v[164:165], 0, s[46:47]
	v_lshl_add_u64 v[14:15], v[164:165], 0, s[48:49]
	v_lshl_add_u64 v[170:171], v[164:165], 0, s[50:51]
	v_lshl_add_u64 v[172:173], v[164:165], 0, s[52:53]
	v_lshl_add_u64 v[174:175], v[164:165], 0, s[58:59]
	v_lshl_add_u64 v[2:3], v[164:165], 0, s[62:63]
	v_lshl_add_u64 v[180:181], s[40:41], 0, v[180:181]
	s_mov_b32 s0, 1
	s_mov_b64 s[64:65], 0
	s_mov_b32 s96, 0
	s_movk_i32 s97, 0x4000
	s_mov_b32 s98, 0x11000
	s_add_i32 m0, s78, s98
	s_add_i32 s3, s98, s80
	global_load_lds_dwordx4 v[180:181], off
	s_add_i32 m0, s3, 0x8000
	s_add_i32 s3, s98, s79
	global_load_lds_dwordx4 v[166:167], off
	s_add_i32 m0, s3, 0x8000
	v_lshl_add_u64 v[180:181], v[180:181], 0, s[42:43]
	global_load_lds_dwordx4 v[168:169], off
	s_waitcnt vmcnt(3) lgkmcnt(0)
	s_barrier
	s_branch .LBB0_305

; __device__ __forceinline__ void diff_unit(const Params& p, LAS unsigned char* lds, int b, int h, int qb, float lam) {
;     ...
;             asm volatile("s_waitcnt vmcnt(0)" ::: "memory");
;             __syncthreads();
.LBB0_304:
	s_sub_i32 s77, s77, 64
	s_add_i32 s0, s0, 1
	s_cmp_lg_u32 s4, s64
	v_lshl_add_u64 v[180:181], v[180:181], 0, s[42:43]
	s_cbranch_scc0 .Lring1_last
	s_waitcnt vmcnt(3) lgkmcnt(0)
	s_barrier
	s_branch .LBB0_305

; #define LAS __attribute__((address_space(3)))
; #define MFMA32(a, b, c) __builtin_amdgcn_mfma_f32_32x32x16_bf16((a), (b), (c), 0, 0, 0)
; #define SCHEDB() __builtin_amdgcn_sched_barrier(0)
; __device__ __forceinline__ void diff_unit(const Params& p, LAS unsigned char* lds, int b, int h, int qb, float lam) {
;     ...
;         for (int jt = 0; jt < NT; ++jt) {
;             const int cur = jt & 1;
;             if (jt + 1 < NT) tile_dma<64>(Kg0 + (size_t)(jt + 1) * 4096, Vg0 + (size_t)(jt + 1) * 8192, lds + A_KOFF + (cur ^ 1) * A_KBUF, lds + A_VOFF + (cur ^ 1) * A_VBUF, wid, lane);
;             if (jt <= mylast) {
;                 const LAS unsigned char* kb = lds + A_KOFF + cur * A_KBUF + c * 128;
;                 const LAS unsigned char* vb = lds + A_VOFF + cur * A_VBUF + c * 128;
;                 f32x16 s0, s1;
;                 {
;                     bf16x8 a[2][2];
;                     { const int co = (0 ^ xk) << 4; a[0][0] = *(const LAS bf16x8*)(kb + co); a[0][1] = *(const LAS bf16x8*)(kb + 4096 + co); }
; #pragma unroll
;                     for (int ks = 0; ks < 4; ++ks) {
;                         if (ks + 1 < 4) { const int co = ((2 * (ks + 1)) ^ xk) << 4; a[(ks + 1) & 1][0] = *(const LAS bf16x8*)(kb + co); a[(ks + 1) & 1][1] = *(const LAS bf16x8*)(kb + 4096 + co); }
;                         if (ks == 0) { s0 = MFMA32(a[0][0], qf[0], negm); s1 = MFMA32(a[0][1], qf[0], negm); }
;                         else { s0 = MFMA32(a[ks & 1][0], qf[ks], s0); s1 = MFMA32(a[ks & 1][1], qf[ks], s1); }
;                         SCHEDB();
;                     }
;                 }
;                 if ((q0 - (64 * jt + 63)) < 91) {
;                     const int idx0 = (q0 + c) - (64 * jt + 16 * hh) + 64;
; #pragma unroll
;                     for (int r = 0; r < 16; ++r) { s0[r] += tab[min(idx0 - r, 255)]; s1[r] += tab[min(idx0 - 32 - r, 255)]; if ((r & 3) == 3) SCHEDB(); }
;                 }
.LBB0_305:
	s_mov_b64 s[10:11], s[64:65]
	s_add_u32 s64, s10, 0x4000
	s_addc_u32 s65, s11, 0
	s_mov_b32 s6, s96
	s_mov_b32 s96, s97
	s_mov_b32 s97, s98
	s_mov_b32 s98, s6
	s_mov_b32 s1, s96
	s_cmp_eq_u32 s4, s64
	s_cbranch_scc1 .Lring1_nodma
	s_add_i32 m0, s78, s6
	s_add_i32 s3, s6, s80
	global_load_lds_dwordx4 v[180:181], off
	v_lshl_add_u64 v[112:113], v[166:167], 0, s[64:65]
	s_add_i32 m0, s3, 0x8000
	s_add_i32 s3, s6, s79
	global_load_lds_dwordx4 v[112:113], off
	v_lshl_add_u64 v[112:113], v[168:169], 0, s[64:65]
	s_add_i32 m0, s3, 0x8000
	s_nop 0
	global_load_lds_dwordx4 v[112:113], off
.Lring1_nodma:
	s_cmp_gt_i32 s0, s76
	s_cbranch_scc1 .LBB0_304
	v_add_u32_e32 v0, s1, v197
	v_add_u32_e32 v116, v0, v203
	ds_read_b128 v[112:115], v116
	ds_read_b128 v[214:217], v116 offset:4096
	s_waitcnt lgkmcnt(0)
	v_mfma_f32_32x32x16_bf16 v[128:143], v[112:115], v[156:159], v[96:111]
	v_add_u32_e32 v112, v0, v205
	ds_read_b128 v[218:221], v112
	ds_read_b128 v[222:225], v112 offset:4096
	v_mfma_f32_32x32x16_bf16 v[112:127], v[214:217], v[156:159], v[96:111]
	s_waitcnt lgkmcnt(0)
	v_mfma_f32_32x32x16_bf16 v[128:143], v[218:221], v[152:155], v[128:143]
	v_add_u32_e32 v213, v0, v206
	ds_read_b128 v[214:217], v213
	ds_read_b128 v[218:221], v213 offset:4096
	v_mfma_f32_32x32x16_bf16 v[112:127], v[222:225], v[152:155], v[112:127]
	s_waitcnt lgkmcnt(0)
	v_mfma_f32_32x32x16_bf16 v[128:143], v[214:217], v[148:151], v[128:143]
	v_add_u32_e32 v213, v0, v207
	ds_read_b128 v[214:217], v213
	ds_read_b128 v[222:225], v213 offset:4096
	v_mfma_f32_32x32x16_bf16 v[112:127], v[218:221], v[148:151], v[112:127]
	s_waitcnt lgkmcnt(0)
	v_mfma_f32_32x32x16_bf16 v[128:143], v[214:217], v[144:147], v[128:143]
	v_mfma_f32_32x32x16_bf16 v[112:127], v[222:225], v[144:147], v[112:127]
	s_add_i32 s1, s77, 0xffffff81
	s_cmpk_gt_i32 s1, 0x5a
	s_cbranch_scc1 .LBB0_308
	v_add_u32_e32 v213, s77, v208
	s_add_i32 s1, 0, 0x10000
	v_min_i32_e32 v216, 0xc0, v213
	v_lshl_add_u32 v217, v216, 2, s1
	v_min_i32_e32 v216, 0xe0, v213
	v_lshl_add_u32 v218, v216, 2, s1
	v_min_i32_e32 v216, 0xc1, v213
	v_lshl_add_u32 v219, v216, 2, s1
	v_min_i32_e32 v216, 0xe1, v213
	v_min_i32_e32 v214, 0xbf, v213
	v_min_i32_e32 v215, 0xdf, v213
	v_lshl_add_u32 v220, v216, 2, s1
	v_min_i32_e32 v216, 0xc2, v213
	v_lshl_add_u32 v214, v214, 2, s1
	v_lshl_add_u32 v215, v215, 2, s1
	v_lshl_add_u32 v221, v216, 2, s1
	v_min_i32_e32 v216, 0xe2, v213
	v_lshl_add_u32 v222, v216, 2, s1
	ds_read_b32 v214, v214 offset:256
	ds_read_b32 v216, v215 offset:128
	ds_read_b32 v215, v217 offset:252
	ds_read_b32 v217, v218 offset:124
	ds_read_b32 v218, v219 offset:248
	ds_read_b32 v220, v220 offset:120
	ds_read_b32 v219, v221 offset:244
	ds_read_b32 v221, v222 offset:116
	v_min_i32_e32 v224, 0xc4, v213
	v_lshl_add_u32 v225, v224, 2, s1
	v_min_i32_e32 v224, 0xe4, v213
	v_lshl_add_u32 v226, v224, 2, s1
	v_min_i32_e32 v224, 0xc5, v213
	v_lshl_add_u32 v227, v224, 2, s1
	v_min_i32_e32 v224, 0xe5, v213
	v_min_i32_e32 v222, 0xc3, v213
	v_min_i32_e32 v223, 0xe3, v213
	v_lshl_add_u32 v228, v224, 2, s1
	v_min_i32_e32 v224, 0xc6, v213
	v_lshl_add_u32 v222, v222, 2, s1
	v_lshl_add_u32 v223, v223, 2, s1
	v_lshl_add_u32 v229, v224, 2, s1
	v_min_i32_e32 v224, 0xe6, v213
	v_lshl_add_u32 v230, v224, 2, s1
	ds_read_b32 v222, v222 offset:240
	ds_read_b32 v224, v223 offset:112
	ds_read_b32 v223, v225 offset:236
	ds_read_b32 v225, v226 offset:108
	ds_read_b32 v226, v227 offset:232
	ds_read_b32 v228, v228 offset:104
	ds_read_b32 v227, v229 offset:228
	ds_read_b32 v229, v230 offset:100
	v_min_i32_e32 v232, 0xc8, v213
	v_lshl_add_u32 v233, v232, 2, s1
	v_min_i32_e32 v232, 0xe8, v213
	v_lshl_add_u32 v234, v232, 2, s1
	v_min_i32_e32 v232, 0xc9, v213
	v_lshl_add_u32 v235, v232, 2, s1
	v_min_i32_e32 v232, 0xe9, v213
	v_min_i32_e32 v230, 0xc7, v213
	v_min_i32_e32 v231, 0xe7, v213
	v_lshl_add_u32 v236, v232, 2, s1
	v_min_i32_e32 v232, 0xca, v213
	v_lshl_add_u32 v230, v230, 2, s1
	v_lshl_add_u32 v231, v231, 2, s1
	v_lshl_add_u32 v237, v232, 2, s1
	v_min_i32_e32 v232, 0xea, v213
	v_lshl_add_u32 v238, v232, 2, s1
	ds_read_b32 v230, v230 offset:224
	ds_read_b32 v232, v231 offset:96
	ds_read_b32 v231, v233 offset:220
	ds_read_b32 v233, v234 offset:92
	ds_read_b32 v234, v235 offset:216
	ds_read_b32 v236, v236 offset:88
	ds_read_b32 v235, v237 offset:212
	ds_read_b32 v237, v238 offset:84
	v_min_i32_e32 v238, 0xcb, v213
	v_lshl_add_u32 v238, v238, 2, s1
	v_min_i32_e32 v239, 0xeb, v213
	v_min_i32_e32 v240, 0xcc, v213
	v_min_i32_e32 v241, 0xec, v213
	v_min_i32_e32 v242, 0xcd, v213
	v_min_i32_e32 v243, 0xed, v213
	v_min_i32_e32 v244, 0xce, v213
	v_min_i32_e32 v213, 0xee, v213
	v_lshl_add_u32 v239, v239, 2, s1
	v_lshl_add_u32 v240, v240, 2, s1
	v_lshl_add_u32 v241, v241, 2, s1
	v_lshl_add_u32 v242, v242, 2, s1
	v_lshl_add_u32 v243, v243, 2, s1
	v_lshl_add_u32 v244, v244, 2, s1
	s_waitcnt lgkmcnt(0)
	v_pk_add_f32 v[130:131], v[130:131], v[218:219]
	v_pk_add_f32 v[128:129], v[128:129], v[214:215]
	v_pk_add_f32 v[134:135], v[134:135], v[226:227]
	v_pk_add_f32 v[132:133], v[132:133], v[222:223]
	v_lshl_add_u32 v213, v213, 2, s1
	ds_read_b32 v214, v238 offset:208
	ds_read_b32 v218, v239 offset:80
	ds_read_b32 v222, v242 offset:200
	ds_read_b32 v223, v244 offset:196
	ds_read_b32 v215, v240 offset:204
	ds_read_b32 v227, v213 offset:68
	ds_read_b32 v226, v243 offset:72
	ds_read_b32 v219, v241 offset:76
	v_pk_add_f32 v[138:139], v[138:139], v[234:235]
	v_pk_add_f32 v[136:137], v[136:137], v[230:231]
	s_waitcnt lgkmcnt(0)
	v_pk_add_f32 v[142:143], v[142:143], v[222:223]
	v_pk_add_f32 v[140:141], v[140:141], v[214:215]
	v_pk_add_f32 v[114:115], v[114:115], v[220:221]
	v_pk_add_f32 v[112:113], v[112:113], v[216:217]
	v_pk_add_f32 v[118:119], v[118:119], v[228:229]
	v_pk_add_f32 v[116:117], v[116:117], v[224:225]
	v_pk_add_f32 v[122:123], v[122:123], v[236:237]
	v_pk_add_f32 v[120:121], v[120:121], v[232:233]
	v_pk_add_f32 v[126:127], v[126:127], v[226:227]
	v_pk_add_f32 v[124:125], v[124:125], v[218:219]

; #define LAS __attribute__((address_space(3)))
; #define MFMA32(a, b, c) __builtin_amdgcn_mfma_f32_32x32x16_bf16((a), (b), (c), 0, 0, 0)
; #define SCHEDB() __builtin_amdgcn_sched_barrier(0)
; __device__ __forceinline__ void diff_unit(const Params& p, LAS unsigned char* lds, int b, int h, int qb, float lam) {
;     ...
;             if (jt <= mylast) {
;                 const LAS unsigned char* kb = lds + A_KOFF + cur * A_KBUF + c * 128;
;                 const LAS unsigned char* vb = lds + A_VOFF + cur * A_VBUF + c * 128;
;                 f32x16 s0, s1;
;                 {
;                     bf16x8 a[2][2];
;                     { const int co = (0 ^ xk) << 4; a[0][0] = *(const LAS bf16x8*)(kb + co); a[0][1] = *(const LAS bf16x8*)(kb + 4096 + co); }
; #pragma unroll
;                     for (int ks = 0; ks < 4; ++ks) {
;                         if (ks + 1 < 4) { const int co = ((2 * (ks + 1)) ^ xk) << 4; a[(ks + 1) & 1][0] = *(const LAS bf16x8*)(kb + co); a[(ks + 1) & 1][1] = *(const LAS bf16x8*)(kb + 4096 + co); }
;                         if (ks == 0) { s0 = MFMA32(a[0][0], qf[0], negm); s1 = MFMA32(a[0][1], qf[0], negm); }
;                         else { s0 = MFMA32(a[ks & 1][0], qf[ks], s0); s1 = MFMA32(a[ks & 1][1], qf[ks], s1); }
;                         SCHEDB();
;                     }
;                 }
;                 if ((q0 - (64 * jt + 63)) < 91) {
;                     const int idx0 = (q0 + c) - (64 * jt + 16 * hh) + 64;
; #pragma unroll
;                     for (int r = 0; r < 16; ++r) { s0[r] += tab[min(idx0 - r, 255)]; s1[r] += tab[min(idx0 - 32 - r, 255)]; if ((r & 3) == 3) SCHEDB(); }
;                 }
.LBB0_310:
	s_or_b32 s0, s66, 3
	s_cmp_gt_i32 s0, s76
	s_cbranch_scc1 .LBB0_267
	s_sub_i32 s99, s97, 0x4000
	v_add_u32_e32 v3, s99, v197
	v_add_u32_e32 v2, s99, v204
	ds_read_b128 v[128:131], v2 offset:16384
	ds_read_b128 v[132:135], v2 offset:20480
	s_waitcnt lgkmcnt(1)
	v_mfma_f32_32x32x16_bf16 v[112:127], v[128:131], v[156:159], v[96:111]
	v_add_u32_e32 v2, s99, v211
	ds_read_b128 v[128:131], v2 offset:16384
	ds_read_b128 v[136:139], v2 offset:20480
	s_waitcnt lgkmcnt(2)
	v_mfma_f32_32x32x16_bf16 v[96:111], v[132:135], v[156:159], v[96:111]
	s_waitcnt lgkmcnt(1)
	v_mfma_f32_32x32x16_bf16 v[112:127], v[128:131], v[152:155], v[112:127]
	v_add_u32_e32 v2, s99, v210
	ds_read_b128 v[128:131], v2 offset:16384
	ds_read_b128 v[132:135], v2 offset:20480
	s_waitcnt lgkmcnt(2)
	v_mfma_f32_32x32x16_bf16 v[96:111], v[136:139], v[152:155], v[96:111]
	s_waitcnt lgkmcnt(1)
	v_mfma_f32_32x32x16_bf16 v[112:127], v[128:131], v[148:151], v[112:127]
	v_add_u32_e32 v2, s99, v209
	ds_read_b128 v[128:131], v2 offset:16384
	ds_read_b128 v[136:139], v2 offset:20480
	s_waitcnt lgkmcnt(2)
	v_mfma_f32_32x32x16_bf16 v[96:111], v[132:135], v[148:151], v[96:111]
	s_waitcnt lgkmcnt(1)
	v_mfma_f32_32x32x16_bf16 v[112:127], v[128:131], v[144:147], v[112:127]
	s_waitcnt lgkmcnt(0)
	v_mfma_f32_32x32x16_bf16 v[96:111], v[136:139], v[144:147], v[96:111]
	s_lshl_b32 s0, s0, 6
	s_sub_i32 s1, s5, s0
	s_cmpk_gt_i32 s1, 0x5a
	s_cbranch_scc1 .LBB0_313
	s_sub_i32 s0, 0, s0
	v_add_u32_e32 v0, s0, v202
	s_add_i32 s0, 0, 0x10000
	v_min_i32_e32 v130, 0xc0, v0
	v_lshl_add_u32 v131, v130, 2, s0
	v_min_i32_e32 v130, 0xe0, v0
	v_lshl_add_u32 v132, v130, 2, s0
	v_min_i32_e32 v130, 0xc1, v0
	v_lshl_add_u32 v133, v130, 2, s0
	v_min_i32_e32 v130, 0xe1, v0
	v_min_i32_e32 v128, 0xbf, v0
	v_min_i32_e32 v129, 0xdf, v0
	v_lshl_add_u32 v134, v130, 2, s0
	v_min_i32_e32 v130, 0xc2, v0
	v_lshl_add_u32 v128, v128, 2, s0
	v_lshl_add_u32 v129, v129, 2, s0
	v_lshl_add_u32 v135, v130, 2, s0
	v_min_i32_e32 v130, 0xe2, v0
	v_lshl_add_u32 v136, v130, 2, s0
	ds_read_b32 v128, v128 offset:256
	ds_read_b32 v130, v129 offset:128
	ds_read_b32 v129, v131 offset:252
	ds_read_b32 v131, v132 offset:124
	ds_read_b32 v132, v133 offset:248
	ds_read_b32 v134, v134 offset:120
	ds_read_b32 v133, v135 offset:244
	ds_read_b32 v135, v136 offset:116
	v_min_i32_e32 v138, 0xc4, v0
	v_lshl_add_u32 v139, v138, 2, s0
	v_min_i32_e32 v138, 0xe4, v0
	v_lshl_add_u32 v140, v138, 2, s0
	v_min_i32_e32 v138, 0xc5, v0
	v_lshl_add_u32 v141, v138, 2, s0
	v_min_i32_e32 v138, 0xe5, v0
	v_min_i32_e32 v136, 0xc3, v0
	v_min_i32_e32 v137, 0xe3, v0
	v_lshl_add_u32 v142, v138, 2, s0
	v_min_i32_e32 v138, 0xc6, v0
	v_lshl_add_u32 v136, v136, 2, s0
	v_lshl_add_u32 v137, v137, 2, s0
	v_lshl_add_u32 v143, v138, 2, s0
	v_min_i32_e32 v138, 0xe6, v0
	v_lshl_add_u32 v144, v138, 2, s0
	ds_read_b32 v136, v136 offset:240
	ds_read_b32 v138, v137 offset:112
	ds_read_b32 v137, v139 offset:236
	ds_read_b32 v139, v140 offset:108
	ds_read_b32 v140, v141 offset:232
	ds_read_b32 v142, v142 offset:104
	ds_read_b32 v141, v143 offset:228
	ds_read_b32 v143, v144 offset:100
	v_min_i32_e32 v146, 0xc8, v0
	v_lshl_add_u32 v147, v146, 2, s0
	v_min_i32_e32 v146, 0xe8, v0
	v_lshl_add_u32 v148, v146, 2, s0
	v_min_i32_e32 v146, 0xc9, v0
	v_lshl_add_u32 v149, v146, 2, s0
	v_min_i32_e32 v146, 0xe9, v0
	v_min_i32_e32 v144, 0xc7, v0
	v_min_i32_e32 v145, 0xe7, v0
	v_lshl_add_u32 v150, v146, 2, s0
	v_min_i32_e32 v146, 0xca, v0
	v_lshl_add_u32 v144, v144, 2, s0
	v_lshl_add_u32 v145, v145, 2, s0
	v_lshl_add_u32 v151, v146, 2, s0
	v_min_i32_e32 v146, 0xea, v0
	v_lshl_add_u32 v152, v146, 2, s0
	ds_read_b32 v144, v144 offset:224
	ds_read_b32 v146, v145 offset:96
	ds_read_b32 v145, v147 offset:220
	ds_read_b32 v147, v148 offset:92
	ds_read_b32 v148, v149 offset:216
	ds_read_b32 v150, v150 offset:88
	ds_read_b32 v149, v151 offset:212
	ds_read_b32 v151, v152 offset:84
	v_min_i32_e32 v152, 0xcb, v0
	v_lshl_add_u32 v152, v152, 2, s0
	v_min_i32_e32 v153, 0xeb, v0
	v_min_i32_e32 v154, 0xcc, v0
	v_min_i32_e32 v155, 0xec, v0
	v_min_i32_e32 v156, 0xcd, v0
	v_min_i32_e32 v157, 0xed, v0
	v_min_i32_e32 v158, 0xce, v0
	v_min_i32_e32 v0, 0xee, v0
	v_lshl_add_u32 v153, v153, 2, s0
	v_lshl_add_u32 v154, v154, 2, s0
	v_lshl_add_u32 v155, v155, 2, s0
	v_lshl_add_u32 v156, v156, 2, s0
	v_lshl_add_u32 v157, v157, 2, s0
	v_lshl_add_u32 v158, v158, 2, s0
	s_waitcnt lgkmcnt(14)
	v_pk_add_f32 v[114:115], v[114:115], v[132:133]
	v_pk_add_f32 v[112:113], v[112:113], v[128:129]
	s_waitcnt lgkmcnt(9)
	v_pk_add_f32 v[118:119], v[118:119], v[140:141]
	v_pk_add_f32 v[116:117], v[116:117], v[136:137]
	v_lshl_add_u32 v0, v0, 2, s0
	ds_read_b32 v128, v152 offset:208
	ds_read_b32 v132, v153 offset:80
	ds_read_b32 v136, v156 offset:200
	ds_read_b32 v137, v158 offset:196
	ds_read_b32 v129, v154 offset:204
	ds_read_b32 v141, v0 offset:68
	ds_read_b32 v140, v157 offset:72
	ds_read_b32 v133, v155 offset:76
	s_waitcnt lgkmcnt(9)
	v_pk_add_f32 v[122:123], v[122:123], v[148:149]
	v_pk_add_f32 v[120:121], v[120:121], v[144:145]
	s_waitcnt lgkmcnt(4)
	v_pk_add_f32 v[126:127], v[126:127], v[136:137]
	s_waitcnt lgkmcnt(3)
	v_pk_add_f32 v[124:125], v[124:125], v[128:129]
	v_pk_add_f32 v[98:99], v[98:99], v[134:135]
	v_pk_add_f32 v[96:97], v[96:97], v[130:131]
	v_pk_add_f32 v[102:103], v[102:103], v[142:143]
	v_pk_add_f32 v[100:101], v[100:101], v[138:139]
	v_pk_add_f32 v[106:107], v[106:107], v[150:151]
	v_pk_add_f32 v[104:105], v[104:105], v[146:147]
	s_waitcnt lgkmcnt(1)
	v_pk_add_f32 v[110:111], v[110:111], v[140:141]
	s_waitcnt lgkmcnt(0)
	v_pk_add_f32 v[108:109], v[108:109], v[132:133]
